# plus: EpiMergeF sel loads batched, hyena filter rows prefetched before the serialized load loop
# speedup vs baseline: 1.0429x; 1.0057x over previous
; __device__ __forceinline__ unsigned cvt_pk_bf16(float lo, float hi) { unsigned r; asm volatile("v_cvt_pk_bf16_f32 %0, %1, %2" : "=v"(r) : "v"(lo), "v"(hi)); return r; }
; __device__ __forceinline__ float bf2f(unsigned b) { return __uint_as_float(b << 16); }
;     __device__ __forceinline__ void operator()(const f32x4 (&acc)[2][2][4][2], const pg8::Unit& u, int wr, int wc, int fr, int fq) const {
;     ...
;         const int row0 = u.pm * 256 + wr * 64 + fr, col0 = u.pn * 256 + wc * 32 + 4 * fq;
; #pragma unroll
;         for (int ai = 0; ai < 2; ++ai)
; #pragma unroll
;             for (int m = 0; m < 4; ++m) { const size_t row = row0 + ai * 128 + m * 16;
; #pragma unroll
;                 for (int bj = 0; bj < 2; ++bj)
; #pragma unroll
;                     for (int n = 0; n < 2; ++n) { const int col = col0 + bj * 128 + n * 16;
;                         const u32x2 sr = *(const u32x2*)(sel + row * 3072 + 2048 + col);
;                         f32x4 v = acc[ai][bj][m][n]; v[0] *= bf2f(sr.x & 0xffffu); v[1] *= bf2f(sr.x >> 16); v[2] *= bf2f(sr.y & 0xffffu); v[3] *= bf2f(sr.y >> 16);
;                         u32x2 w; w.x = pg8::cvt_pk_bf16(v[0], v[1]); w.y = pg8::cvt_pk_bf16(v[2], v[3]); *(u32x2*)(outpre + row * 1024 + col) = w; } }
.LBB0_131:
	v_mov_b32_e32 v96, v155
	v_mov_b32_e32 v98, v154
	v_readlane_b32 s4, v251, 28
	v_add_u32_e32 v144, s93, v98
	v_lshl_add_u32 v98, v96, 2, s84
	v_readlane_b32 s5, v251, 29
	v_ashrrev_i32_e32 v99, 31, v98
	v_lshlrev_b64 v[98:99], 1, v[98:99]
	v_mov_b64_e32 v[146:147], s[4:5]
	s_mov_b64 s[6:7], 0x1000
	v_readlane_b32 s4, v253, 7
	v_readlane_b32 s5, v253, 8
	v_mad_i64_i32 v[150:151], s[38:39], v144, s78, v[146:147]
	v_lshl_add_u64 v[150:151], v[150:151], 0, v[98:99]
	v_lshl_add_u64 v[150:151], v[150:151], 0, s[6:7]
	global_load_dwordx2 v[160:161], v[150:151], off
	global_load_dwordx2 v[162:163], v[150:151], off offset:32
	global_load_dwordx2 v[164:165], v[150:151], off offset:256
	global_load_dwordx2 v[166:167], v[150:151], off offset:288
	v_add_u32_e32 v150, 16, v144
	v_mad_i64_i32 v[150:151], s[38:39], v150, s78, v[146:147]
	v_lshl_add_u64 v[150:151], v[150:151], 0, v[98:99]
	v_lshl_add_u64 v[150:151], v[150:151], 0, s[6:7]
	global_load_dwordx2 v[168:169], v[150:151], off
	global_load_dwordx2 v[170:171], v[150:151], off offset:32
	global_load_dwordx2 v[172:173], v[150:151], off offset:256
	global_load_dwordx2 v[174:175], v[150:151], off offset:288
	v_add_u32_e32 v150, 32, v144
	v_mad_i64_i32 v[150:151], s[38:39], v150, s78, v[146:147]
	v_lshl_add_u64 v[150:151], v[150:151], 0, v[98:99]
	v_lshl_add_u64 v[150:151], v[150:151], 0, s[6:7]
	global_load_dwordx2 v[176:177], v[150:151], off
	global_load_dwordx2 v[178:179], v[150:151], off offset:32
	global_load_dwordx2 v[180:181], v[150:151], off offset:256
	global_load_dwordx2 v[182:183], v[150:151], off offset:288
	v_add_u32_e32 v150, 48, v144
	v_mad_i64_i32 v[150:151], s[38:39], v150, s78, v[146:147]
	v_lshl_add_u64 v[150:151], v[150:151], 0, v[98:99]
	v_lshl_add_u64 v[150:151], v[150:151], 0, s[6:7]
	global_load_dwordx2 v[184:185], v[150:151], off
	global_load_dwordx2 v[186:187], v[150:151], off offset:32
	global_load_dwordx2 v[188:189], v[150:151], off offset:256
	global_load_dwordx2 v[190:191], v[150:151], off offset:288
	v_add_u32_e32 v150, 128, v144
	v_mad_i64_i32 v[150:151], s[38:39], v150, s78, v[146:147]
	v_lshl_add_u64 v[150:151], v[150:151], 0, v[98:99]
	v_lshl_add_u64 v[150:151], v[150:151], 0, s[6:7]
	global_load_dwordx2 v[192:193], v[150:151], off
	global_load_dwordx2 v[194:195], v[150:151], off offset:32
	global_load_dwordx2 v[196:197], v[150:151], off offset:256
	global_load_dwordx2 v[198:199], v[150:151], off offset:288
	v_add_u32_e32 v150, 144, v144
	v_mad_i64_i32 v[150:151], s[38:39], v150, s78, v[146:147]
	v_lshl_add_u64 v[150:151], v[150:151], 0, v[98:99]
	v_lshl_add_u64 v[150:151], v[150:151], 0, s[6:7]
	global_load_dwordx2 v[200:201], v[150:151], off
	global_load_dwordx2 v[202:203], v[150:151], off offset:32
	global_load_dwordx2 v[204:205], v[150:151], off offset:256
	global_load_dwordx2 v[206:207], v[150:151], off offset:288
	v_add_u32_e32 v150, 160, v144
	v_mad_i64_i32 v[150:151], s[38:39], v150, s78, v[146:147]
	v_lshl_add_u64 v[150:151], v[150:151], 0, v[98:99]
	v_lshl_add_u64 v[150:151], v[150:151], 0, s[6:7]
	global_load_dwordx2 v[230:231], v[150:151], off
	global_load_dwordx2 v[232:233], v[150:151], off offset:32
	global_load_dwordx2 v[234:235], v[150:151], off offset:256
	global_load_dwordx2 v[236:237], v[150:151], off offset:288
	v_add_u32_e32 v150, 176, v144
	v_mad_i64_i32 v[150:151], s[38:39], v150, s78, v[146:147]
	v_lshl_add_u64 v[150:151], v[150:151], 0, v[98:99]
	v_lshl_add_u64 v[150:151], v[150:151], 0, s[6:7]
	global_load_dwordx2 v[238:239], v[150:151], off
	global_load_dwordx2 v[208:209], v[150:151], off offset:32
	global_load_dwordx2 v[158:159], v[150:151], off offset:256
	global_load_dwordx2 v[152:153], v[150:151], off offset:288
	v_mov_b32_e32 v140, v144
	v_ashrrev_i32_e32 v141, 31, v140
	v_lshlrev_b64 v[140:141], 11, v[140:141]
	v_lshl_add_u64 v[140:141], s[4:5], 0, v[140:141]
	v_lshl_add_u64 v[140:141], v[140:141], 0, v[98:99]
	s_waitcnt vmcnt(31)
	v_lshlrev_b32_e32 v148, 16, v160
	v_and_b32_e32 v149, 0xffff0000, v160
	v_lshlrev_b32_e32 v150, 16, v161
	v_and_b32_e32 v151, 0xffff0000, v161
	v_mul_f32_e32 v148, v128, v148
	v_mul_f32_e32 v149, v129, v149
	v_mul_f32_e32 v150, v130, v150
	v_mul_f32_e32 v151, v131, v151
	v_cvt_pk_bf16_f32 v138, v148, v149
	v_cvt_pk_bf16_f32 v139, v150, v151
	global_store_dwordx2 v[140:141], v[138:139], off
	s_waitcnt vmcnt(31)
	v_lshlrev_b32_e32 v148, 16, v162
	v_and_b32_e32 v149, 0xffff0000, v162
	v_lshlrev_b32_e32 v150, 16, v163
	v_and_b32_e32 v151, 0xffff0000, v163
	v_mul_f32_e32 v148, v124, v148
	v_mul_f32_e32 v149, v125, v149
	v_mul_f32_e32 v150, v126, v150
	v_mul_f32_e32 v151, v127, v151
	v_cvt_pk_bf16_f32 v138, v148, v149
	v_cvt_pk_bf16_f32 v139, v150, v151
	global_store_dwordx2 v[140:141], v[138:139], off offset:32
	s_waitcnt vmcnt(31)
	v_lshlrev_b32_e32 v148, 16, v164
	v_and_b32_e32 v149, 0xffff0000, v164
	v_lshlrev_b32_e32 v150, 16, v165
	v_and_b32_e32 v151, 0xffff0000, v165
	v_mul_f32_e32 v148, v120, v148
	v_mul_f32_e32 v149, v121, v149
	v_mul_f32_e32 v150, v122, v150
	v_mul_f32_e32 v151, v123, v151
	v_cvt_pk_bf16_f32 v138, v148, v149
	v_cvt_pk_bf16_f32 v139, v150, v151
	global_store_dwordx2 v[140:141], v[138:139], off offset:256
	s_waitcnt vmcnt(31)
	v_lshlrev_b32_e32 v148, 16, v166
	v_and_b32_e32 v149, 0xffff0000, v166
	v_lshlrev_b32_e32 v150, 16, v167
	v_and_b32_e32 v151, 0xffff0000, v167
	v_mul_f32_e32 v148, v116, v148
	v_mul_f32_e32 v149, v117, v149
	v_mul_f32_e32 v150, v118, v150
	v_mul_f32_e32 v151, v119, v151
	v_cvt_pk_bf16_f32 v138, v148, v149
	v_cvt_pk_bf16_f32 v139, v150, v151
	global_store_dwordx2 v[140:141], v[138:139], off offset:288
	v_add_u32_e32 v140, 16, v144
	v_ashrrev_i32_e32 v141, 31, v140
	v_lshlrev_b64 v[140:141], 11, v[140:141]
	v_lshl_add_u64 v[140:141], s[4:5], 0, v[140:141]
	v_lshl_add_u64 v[140:141], v[140:141], 0, v[98:99]
	s_waitcnt vmcnt(31)
; __device__ __forceinline__ unsigned cvt_pk_bf16(float lo, float hi) { unsigned r; asm volatile("v_cvt_pk_bf16_f32 %0, %1, %2" : "=v"(r) : "v"(lo), "v"(hi)); return r; }
; __device__ __forceinline__ float bf2f(unsigned b) { return __uint_as_float(b << 16); }
;     __device__ __forceinline__ void operator()(const f32x4 (&acc)[2][2][4][2], const pg8::Unit& u, int wr, int wc, int fr, int fq) const {
;     ...
;         const int row0 = u.pm * 256 + wr * 64 + fr, col0 = u.pn * 256 + wc * 32 + 4 * fq;
; #pragma unroll
;         for (int ai = 0; ai < 2; ++ai)
; #pragma unroll
;             for (int m = 0; m < 4; ++m) { const size_t row = row0 + ai * 128 + m * 16;
; #pragma unroll
;                 for (int bj = 0; bj < 2; ++bj)
; #pragma unroll
;                     for (int n = 0; n < 2; ++n) { const int col = col0 + bj * 128 + n * 16;
;                         const u32x2 sr = *(const u32x2*)(sel + row * 3072 + 2048 + col);
;                         f32x4 v = acc[ai][bj][m][n]; v[0] *= bf2f(sr.x & 0xffffu); v[1] *= bf2f(sr.x >> 16); v[2] *= bf2f(sr.y & 0xffffu); v[3] *= bf2f(sr.y >> 16);
;                         u32x2 w; w.x = pg8::cvt_pk_bf16(v[0], v[1]); w.y = pg8::cvt_pk_bf16(v[2], v[3]); *(u32x2*)(outpre + row * 1024 + col) = w; } }
	v_lshlrev_b32_e32 v148, 16, v168
	v_and_b32_e32 v149, 0xffff0000, v168
	v_lshlrev_b32_e32 v150, 16, v169
	v_and_b32_e32 v151, 0xffff0000, v169
	v_mul_f32_e32 v148, v112, v148
	v_mul_f32_e32 v149, v113, v149
	v_mul_f32_e32 v150, v114, v150
	v_mul_f32_e32 v151, v115, v151
	v_cvt_pk_bf16_f32 v138, v148, v149
	v_cvt_pk_bf16_f32 v139, v150, v151
	global_store_dwordx2 v[140:141], v[138:139], off
	s_waitcnt vmcnt(31)
	v_lshlrev_b32_e32 v148, 16, v170
	v_and_b32_e32 v149, 0xffff0000, v170
	v_lshlrev_b32_e32 v150, 16, v171
	v_and_b32_e32 v151, 0xffff0000, v171
	v_mul_f32_e32 v148, v108, v148
	v_mul_f32_e32 v149, v109, v149
	v_mul_f32_e32 v150, v110, v150
	v_mul_f32_e32 v151, v111, v151
	v_cvt_pk_bf16_f32 v138, v148, v149
	v_cvt_pk_bf16_f32 v139, v150, v151
	global_store_dwordx2 v[140:141], v[138:139], off offset:32
	s_waitcnt vmcnt(31)
	v_lshlrev_b32_e32 v148, 16, v172
	v_and_b32_e32 v149, 0xffff0000, v172
	v_lshlrev_b32_e32 v150, 16, v173
	v_and_b32_e32 v151, 0xffff0000, v173
	v_mul_f32_e32 v148, v104, v148
	v_mul_f32_e32 v149, v105, v149
	v_mul_f32_e32 v150, v106, v150
	v_mul_f32_e32 v151, v107, v151
	v_cvt_pk_bf16_f32 v138, v148, v149
	v_cvt_pk_bf16_f32 v139, v150, v151
	global_store_dwordx2 v[140:141], v[138:139], off offset:256
	s_waitcnt vmcnt(31)
	v_lshlrev_b32_e32 v148, 16, v174
	v_and_b32_e32 v149, 0xffff0000, v174
	v_lshlrev_b32_e32 v150, 16, v175
	v_and_b32_e32 v151, 0xffff0000, v175
	v_mul_f32_e32 v148, v100, v148
	v_mul_f32_e32 v149, v101, v149
	v_mul_f32_e32 v150, v102, v150
	v_mul_f32_e32 v151, v103, v151
	v_cvt_pk_bf16_f32 v138, v148, v149
	v_cvt_pk_bf16_f32 v139, v150, v151
	global_store_dwordx2 v[140:141], v[138:139], off offset:288
	v_add_u32_e32 v140, 32, v144
	v_ashrrev_i32_e32 v141, 31, v140
	v_lshlrev_b64 v[140:141], 11, v[140:141]
	v_lshl_add_u64 v[140:141], s[4:5], 0, v[140:141]
	v_lshl_add_u64 v[140:141], v[140:141], 0, v[98:99]
	s_waitcnt vmcnt(31)
	v_lshlrev_b32_e32 v148, 16, v176
	v_and_b32_e32 v149, 0xffff0000, v176
	v_lshlrev_b32_e32 v150, 16, v177
	v_and_b32_e32 v151, 0xffff0000, v177
	v_mul_f32_e32 v148, v92, v148
	v_mul_f32_e32 v149, v93, v149
	v_mul_f32_e32 v150, v94, v150
	v_mul_f32_e32 v151, v95, v151
	v_cvt_pk_bf16_f32 v138, v148, v149
	v_cvt_pk_bf16_f32 v139, v150, v151
	global_store_dwordx2 v[140:141], v[138:139], off
	s_waitcnt vmcnt(31)
	v_lshlrev_b32_e32 v148, 16, v178
	v_and_b32_e32 v149, 0xffff0000, v178
	v_lshlrev_b32_e32 v150, 16, v179
	v_and_b32_e32 v151, 0xffff0000, v179
	v_mul_f32_e32 v148, v88, v148
	v_mul_f32_e32 v149, v89, v149
	v_mul_f32_e32 v150, v90, v150
	v_mul_f32_e32 v151, v91, v151
	v_cvt_pk_bf16_f32 v138, v148, v149
	v_cvt_pk_bf16_f32 v139, v150, v151
	global_store_dwordx2 v[140:141], v[138:139], off offset:32
	s_waitcnt vmcnt(31)
	v_lshlrev_b32_e32 v148, 16, v180
	v_and_b32_e32 v149, 0xffff0000, v180
	v_lshlrev_b32_e32 v150, 16, v181
	v_and_b32_e32 v151, 0xffff0000, v181
	v_mul_f32_e32 v148, v84, v148
	v_mul_f32_e32 v149, v85, v149
	v_mul_f32_e32 v150, v86, v150
	v_mul_f32_e32 v151, v87, v151
	v_cvt_pk_bf16_f32 v138, v148, v149
	v_cvt_pk_bf16_f32 v139, v150, v151
	global_store_dwordx2 v[140:141], v[138:139], off offset:256
	s_waitcnt vmcnt(31)
	v_lshlrev_b32_e32 v148, 16, v182
	v_and_b32_e32 v149, 0xffff0000, v182
	v_lshlrev_b32_e32 v150, 16, v183
	v_and_b32_e32 v151, 0xffff0000, v183
	v_mul_f32_e32 v148, v80, v148
	v_mul_f32_e32 v149, v81, v149
	v_mul_f32_e32 v150, v82, v150
	v_mul_f32_e32 v151, v83, v151
	v_cvt_pk_bf16_f32 v138, v148, v149
	v_cvt_pk_bf16_f32 v139, v150, v151
	global_store_dwordx2 v[140:141], v[138:139], off offset:288
	v_add_u32_e32 v140, 48, v144
	v_ashrrev_i32_e32 v141, 31, v140
	v_lshlrev_b64 v[140:141], 11, v[140:141]
	v_lshl_add_u64 v[140:141], s[4:5], 0, v[140:141]
	v_lshl_add_u64 v[140:141], v[140:141], 0, v[98:99]
	s_waitcnt vmcnt(31)
	v_lshlrev_b32_e32 v148, 16, v184
	v_and_b32_e32 v149, 0xffff0000, v184
	v_lshlrev_b32_e32 v150, 16, v185
	v_and_b32_e32 v151, 0xffff0000, v185
	v_mul_f32_e32 v148, v76, v148
	v_mul_f32_e32 v149, v77, v149
	v_mul_f32_e32 v150, v78, v150
	v_mul_f32_e32 v151, v79, v151
	v_cvt_pk_bf16_f32 v138, v148, v149
	v_cvt_pk_bf16_f32 v139, v150, v151
	global_store_dwordx2 v[140:141], v[138:139], off
	s_waitcnt vmcnt(31)
	v_lshlrev_b32_e32 v148, 16, v186
	v_and_b32_e32 v149, 0xffff0000, v186
	v_lshlrev_b32_e32 v150, 16, v187
	v_and_b32_e32 v151, 0xffff0000, v187
	v_mul_f32_e32 v148, v72, v148
	v_mul_f32_e32 v149, v73, v149
	v_mul_f32_e32 v150, v74, v150
	v_mul_f32_e32 v151, v75, v151
	v_cvt_pk_bf16_f32 v138, v148, v149
	v_cvt_pk_bf16_f32 v139, v150, v151
	global_store_dwordx2 v[140:141], v[138:139], off offset:32
	s_waitcnt vmcnt(31)
	v_lshlrev_b32_e32 v148, 16, v188
	v_and_b32_e32 v149, 0xffff0000, v188
	v_lshlrev_b32_e32 v150, 16, v189
	v_and_b32_e32 v151, 0xffff0000, v189
	v_mul_f32_e32 v148, v68, v148
	v_mul_f32_e32 v149, v69, v149
	v_mul_f32_e32 v150, v70, v150
	v_mul_f32_e32 v151, v71, v151
	v_cvt_pk_bf16_f32 v138, v148, v149
	v_cvt_pk_bf16_f32 v139, v150, v151
	global_store_dwordx2 v[140:141], v[138:139], off offset:256
	s_waitcnt vmcnt(31)
	v_lshlrev_b32_e32 v148, 16, v190
	v_and_b32_e32 v149, 0xffff0000, v190
	v_lshlrev_b32_e32 v150, 16, v191
	v_and_b32_e32 v151, 0xffff0000, v191
	v_mul_f32_e32 v148, v64, v148
	v_mul_f32_e32 v149, v65, v149
	v_mul_f32_e32 v150, v66, v150
	v_mul_f32_e32 v151, v67, v151
	v_cvt_pk_bf16_f32 v138, v148, v149
	v_cvt_pk_bf16_f32 v139, v150, v151
	global_store_dwordx2 v[140:141], v[138:139], off offset:288
	v_add_u32_e32 v140, 128, v144
	v_ashrrev_i32_e32 v141, 31, v140
	v_lshlrev_b64 v[140:141], 11, v[140:141]
	v_lshl_add_u64 v[140:141], s[4:5], 0, v[140:141]
	v_lshl_add_u64 v[140:141], v[140:141], 0, v[98:99]
	s_waitcnt vmcnt(31)
; __device__ __forceinline__ unsigned cvt_pk_bf16(float lo, float hi) { unsigned r; asm volatile("v_cvt_pk_bf16_f32 %0, %1, %2" : "=v"(r) : "v"(lo), "v"(hi)); return r; }
; __device__ __forceinline__ float bf2f(unsigned b) { return __uint_as_float(b << 16); }
;     __device__ __forceinline__ void operator()(const f32x4 (&acc)[2][2][4][2], const pg8::Unit& u, int wr, int wc, int fr, int fq) const {
;     ...
;         const int row0 = u.pm * 256 + wr * 64 + fr, col0 = u.pn * 256 + wc * 32 + 4 * fq;
; #pragma unroll
;         for (int ai = 0; ai < 2; ++ai)
; #pragma unroll
;             for (int m = 0; m < 4; ++m) { const size_t row = row0 + ai * 128 + m * 16;
; #pragma unroll
;                 for (int bj = 0; bj < 2; ++bj)
; #pragma unroll
;                     for (int n = 0; n < 2; ++n) { const int col = col0 + bj * 128 + n * 16;
;                         const u32x2 sr = *(const u32x2*)(sel + row * 3072 + 2048 + col);
;                         f32x4 v = acc[ai][bj][m][n]; v[0] *= bf2f(sr.x & 0xffffu); v[1] *= bf2f(sr.x >> 16); v[2] *= bf2f(sr.y & 0xffffu); v[3] *= bf2f(sr.y >> 16);
;                         u32x2 w; w.x = pg8::cvt_pk_bf16(v[0], v[1]); w.y = pg8::cvt_pk_bf16(v[2], v[3]); *(u32x2*)(outpre + row * 1024 + col) = w; } }
	v_lshlrev_b32_e32 v148, 16, v192
	v_and_b32_e32 v149, 0xffff0000, v192
	v_lshlrev_b32_e32 v150, 16, v193
	v_and_b32_e32 v151, 0xffff0000, v193
	v_mul_f32_e32 v148, v60, v148
	v_mul_f32_e32 v149, v61, v149
	v_mul_f32_e32 v150, v62, v150
	v_mul_f32_e32 v151, v63, v151
	v_cvt_pk_bf16_f32 v138, v148, v149
	v_cvt_pk_bf16_f32 v139, v150, v151
	global_store_dwordx2 v[140:141], v[138:139], off
	s_waitcnt vmcnt(31)
	v_lshlrev_b32_e32 v148, 16, v194
	v_and_b32_e32 v149, 0xffff0000, v194
	v_lshlrev_b32_e32 v150, 16, v195
	v_and_b32_e32 v151, 0xffff0000, v195
	v_mul_f32_e32 v148, v56, v148
	v_mul_f32_e32 v149, v57, v149
	v_mul_f32_e32 v150, v58, v150
	v_mul_f32_e32 v151, v59, v151
	v_cvt_pk_bf16_f32 v138, v148, v149
	v_cvt_pk_bf16_f32 v139, v150, v151
	global_store_dwordx2 v[140:141], v[138:139], off offset:32
	s_waitcnt vmcnt(31)
	v_lshlrev_b32_e32 v148, 16, v196
	v_and_b32_e32 v149, 0xffff0000, v196
	v_lshlrev_b32_e32 v150, 16, v197
	v_and_b32_e32 v151, 0xffff0000, v197
	v_mul_f32_e32 v148, v52, v148
	v_mul_f32_e32 v149, v53, v149
	v_mul_f32_e32 v150, v54, v150
	v_mul_f32_e32 v151, v55, v151
	v_cvt_pk_bf16_f32 v138, v148, v149
	v_cvt_pk_bf16_f32 v139, v150, v151
	global_store_dwordx2 v[140:141], v[138:139], off offset:256
	s_waitcnt vmcnt(31)
	v_lshlrev_b32_e32 v148, 16, v198
	v_and_b32_e32 v149, 0xffff0000, v198
	v_lshlrev_b32_e32 v150, 16, v199
	v_and_b32_e32 v151, 0xffff0000, v199
	v_mul_f32_e32 v148, v48, v148
	v_mul_f32_e32 v149, v49, v149
	v_mul_f32_e32 v150, v50, v150
	v_mul_f32_e32 v151, v51, v151
	v_cvt_pk_bf16_f32 v138, v148, v149
	v_cvt_pk_bf16_f32 v139, v150, v151
	global_store_dwordx2 v[140:141], v[138:139], off offset:288
	v_add_u32_e32 v140, 144, v144
	v_ashrrev_i32_e32 v141, 31, v140
	v_lshlrev_b64 v[140:141], 11, v[140:141]
	v_lshl_add_u64 v[140:141], s[4:5], 0, v[140:141]
	v_lshl_add_u64 v[140:141], v[140:141], 0, v[98:99]
	s_waitcnt vmcnt(31)
	v_lshlrev_b32_e32 v148, 16, v200
	v_and_b32_e32 v149, 0xffff0000, v200
	v_lshlrev_b32_e32 v150, 16, v201
	v_and_b32_e32 v151, 0xffff0000, v201
	v_mul_f32_e32 v148, v44, v148
	v_mul_f32_e32 v149, v45, v149
	v_mul_f32_e32 v150, v46, v150
	v_mul_f32_e32 v151, v47, v151
	v_cvt_pk_bf16_f32 v138, v148, v149
	v_cvt_pk_bf16_f32 v139, v150, v151
	global_store_dwordx2 v[140:141], v[138:139], off
	s_waitcnt vmcnt(31)
	v_lshlrev_b32_e32 v148, 16, v202
	v_and_b32_e32 v149, 0xffff0000, v202
	v_lshlrev_b32_e32 v150, 16, v203
	v_and_b32_e32 v151, 0xffff0000, v203
	v_mul_f32_e32 v148, v40, v148
	v_mul_f32_e32 v149, v41, v149
	v_mul_f32_e32 v150, v42, v150
	v_mul_f32_e32 v151, v43, v151
	v_cvt_pk_bf16_f32 v138, v148, v149
	v_cvt_pk_bf16_f32 v139, v150, v151
	global_store_dwordx2 v[140:141], v[138:139], off offset:32
	s_waitcnt vmcnt(31)
	v_lshlrev_b32_e32 v148, 16, v204
	v_and_b32_e32 v149, 0xffff0000, v204
	v_lshlrev_b32_e32 v150, 16, v205
	v_and_b32_e32 v151, 0xffff0000, v205
	v_mul_f32_e32 v148, v36, v148
	v_mul_f32_e32 v149, v37, v149
	v_mul_f32_e32 v150, v38, v150
	v_mul_f32_e32 v151, v39, v151
	v_cvt_pk_bf16_f32 v138, v148, v149
	v_cvt_pk_bf16_f32 v139, v150, v151
	global_store_dwordx2 v[140:141], v[138:139], off offset:256
	s_waitcnt vmcnt(31)
	v_lshlrev_b32_e32 v148, 16, v206
	v_and_b32_e32 v149, 0xffff0000, v206
	v_lshlrev_b32_e32 v150, 16, v207
	v_and_b32_e32 v151, 0xffff0000, v207
	v_mul_f32_e32 v148, v32, v148
	v_mul_f32_e32 v149, v33, v149
	v_mul_f32_e32 v150, v34, v150
	v_mul_f32_e32 v151, v35, v151
	v_cvt_pk_bf16_f32 v138, v148, v149
	v_cvt_pk_bf16_f32 v139, v150, v151
	global_store_dwordx2 v[140:141], v[138:139], off offset:288
	v_add_u32_e32 v140, 160, v144
	v_ashrrev_i32_e32 v141, 31, v140
	v_lshlrev_b64 v[140:141], 11, v[140:141]
	v_lshl_add_u64 v[140:141], s[4:5], 0, v[140:141]
	v_lshl_add_u64 v[140:141], v[140:141], 0, v[98:99]
	s_waitcnt vmcnt(31)
; __device__ __forceinline__ unsigned cvt_pk_bf16(float lo, float hi) { unsigned r; asm volatile("v_cvt_pk_bf16_f32 %0, %1, %2" : "=v"(r) : "v"(lo), "v"(hi)); return r; }
; __device__ __forceinline__ float bf2f(unsigned b) { return __uint_as_float(b << 16); }
;     __device__ __forceinline__ void operator()(const f32x4 (&acc)[2][2][4][2], const pg8::Unit& u, int wr, int wc, int fr, int fq) const {
;     ...
;         const int row0 = u.pm * 256 + wr * 64 + fr, col0 = u.pn * 256 + wc * 32 + 4 * fq;
; #pragma unroll
;         for (int ai = 0; ai < 2; ++ai)
; #pragma unroll
;             for (int m = 0; m < 4; ++m) { const size_t row = row0 + ai * 128 + m * 16;
; #pragma unroll
;                 for (int bj = 0; bj < 2; ++bj)
; #pragma unroll
;                     for (int n = 0; n < 2; ++n) { const int col = col0 + bj * 128 + n * 16;
;                         const u32x2 sr = *(const u32x2*)(sel + row * 3072 + 2048 + col);
;                         f32x4 v = acc[ai][bj][m][n]; v[0] *= bf2f(sr.x & 0xffffu); v[1] *= bf2f(sr.x >> 16); v[2] *= bf2f(sr.y & 0xffffu); v[3] *= bf2f(sr.y >> 16);
;                         u32x2 w; w.x = pg8::cvt_pk_bf16(v[0], v[1]); w.y = pg8::cvt_pk_bf16(v[2], v[3]); *(u32x2*)(outpre + row * 1024 + col) = w; } }
	v_lshlrev_b32_e32 v148, 16, v230
	v_and_b32_e32 v149, 0xffff0000, v230
	v_lshlrev_b32_e32 v150, 16, v231
	v_and_b32_e32 v151, 0xffff0000, v231
	v_mul_f32_e32 v148, v28, v148
	v_mul_f32_e32 v149, v29, v149
	v_mul_f32_e32 v150, v30, v150
	v_mul_f32_e32 v151, v31, v151
	v_cvt_pk_bf16_f32 v138, v148, v149
	v_cvt_pk_bf16_f32 v139, v150, v151
	global_store_dwordx2 v[140:141], v[138:139], off
	s_waitcnt vmcnt(31)
	v_lshlrev_b32_e32 v148, 16, v232
	v_and_b32_e32 v149, 0xffff0000, v232
	v_lshlrev_b32_e32 v150, 16, v233
	v_and_b32_e32 v151, 0xffff0000, v233
	v_mul_f32_e32 v148, v24, v148
	v_mul_f32_e32 v149, v25, v149
	v_mul_f32_e32 v150, v26, v150
	v_mul_f32_e32 v151, v27, v151
	v_cvt_pk_bf16_f32 v138, v148, v149
	v_cvt_pk_bf16_f32 v139, v150, v151
	global_store_dwordx2 v[140:141], v[138:139], off offset:32
	s_waitcnt vmcnt(31)
	v_lshlrev_b32_e32 v148, 16, v234
	v_and_b32_e32 v149, 0xffff0000, v234
	v_lshlrev_b32_e32 v150, 16, v235
	v_and_b32_e32 v151, 0xffff0000, v235
	v_mul_f32_e32 v148, v20, v148
	v_mul_f32_e32 v149, v21, v149
	v_mul_f32_e32 v150, v22, v150
	v_mul_f32_e32 v151, v23, v151
	v_cvt_pk_bf16_f32 v138, v148, v149
	v_cvt_pk_bf16_f32 v139, v150, v151
	global_store_dwordx2 v[140:141], v[138:139], off offset:256
	s_waitcnt vmcnt(31)
	v_lshlrev_b32_e32 v148, 16, v236
	v_and_b32_e32 v149, 0xffff0000, v236
	v_lshlrev_b32_e32 v150, 16, v237
	v_and_b32_e32 v151, 0xffff0000, v237
	v_mul_f32_e32 v148, v16, v148
	v_mul_f32_e32 v149, v17, v149
	v_mul_f32_e32 v150, v18, v150
	v_mul_f32_e32 v151, v19, v151
	v_cvt_pk_bf16_f32 v138, v148, v149
	v_cvt_pk_bf16_f32 v139, v150, v151
	global_store_dwordx2 v[140:141], v[138:139], off offset:288
	v_add_u32_e32 v140, 176, v144
	v_ashrrev_i32_e32 v141, 31, v140
	v_lshlrev_b64 v[140:141], 11, v[140:141]
	v_lshl_add_u64 v[140:141], s[4:5], 0, v[140:141]
	v_lshl_add_u64 v[140:141], v[140:141], 0, v[98:99]
	s_waitcnt vmcnt(31)
	v_lshlrev_b32_e32 v148, 16, v238
	v_and_b32_e32 v149, 0xffff0000, v238
	v_lshlrev_b32_e32 v150, 16, v239
	v_and_b32_e32 v151, 0xffff0000, v239
	v_mul_f32_e32 v148, v12, v148
	v_mul_f32_e32 v149, v13, v149
	v_mul_f32_e32 v150, v14, v150
	v_mul_f32_e32 v151, v15, v151
	v_cvt_pk_bf16_f32 v138, v148, v149
	v_cvt_pk_bf16_f32 v139, v150, v151
	global_store_dwordx2 v[140:141], v[138:139], off
	s_waitcnt vmcnt(31)
	v_lshlrev_b32_e32 v148, 16, v208
	v_and_b32_e32 v149, 0xffff0000, v208
	v_lshlrev_b32_e32 v150, 16, v209
	v_and_b32_e32 v151, 0xffff0000, v209
	v_mul_f32_e32 v148, v8, v148
	v_mul_f32_e32 v149, v9, v149
	v_mul_f32_e32 v150, v10, v150
	v_mul_f32_e32 v151, v11, v151
	v_cvt_pk_bf16_f32 v138, v148, v149
	v_cvt_pk_bf16_f32 v139, v150, v151
	global_store_dwordx2 v[140:141], v[138:139], off offset:32
	s_waitcnt vmcnt(31)
	v_lshlrev_b32_e32 v148, 16, v158
	v_and_b32_e32 v149, 0xffff0000, v158
	v_lshlrev_b32_e32 v150, 16, v159
	v_and_b32_e32 v151, 0xffff0000, v159
	v_mul_f32_e32 v148, v4, v148
	v_mul_f32_e32 v149, v5, v149
	v_mul_f32_e32 v150, v6, v150
	v_mul_f32_e32 v151, v7, v151
	v_cvt_pk_bf16_f32 v138, v148, v149
	v_cvt_pk_bf16_f32 v139, v150, v151
	global_store_dwordx2 v[140:141], v[138:139], off offset:256
	s_waitcnt vmcnt(31)
	v_lshlrev_b32_e32 v148, 16, v152
	v_and_b32_e32 v149, 0xffff0000, v152
	v_lshlrev_b32_e32 v150, 16, v153
	v_and_b32_e32 v151, 0xffff0000, v153
	v_mul_f32_e32 v148, v0, v148
	v_mul_f32_e32 v149, v1, v149
	v_mul_f32_e32 v150, v2, v150
	v_mul_f32_e32 v151, v3, v151
	v_cvt_pk_bf16_f32 v138, v148, v149
	v_cvt_pk_bf16_f32 v139, v150, v151
	global_store_dwordx2 v[140:141], v[138:139], off offset:288
	s_and_b64 vcc, exec, s[40:41]
	s_mov_b64 s[40:41], -1
	s_cbranch_vccnz .LBB0_108
	s_andn2_b64 vcc, exec, s[34:35]
	s_cbranch_vccnz .LBB0_107
	s_barrier
	s_branch .LBB0_107

; __device__ __forceinline__ void hyena_channel(const Params& p, int l, int c, unsigned char* lds, int wid0) {
;     ...
;             const float* ff = filt + (size_t)c * SEQ; const float* fb = filt + (size_t)(512 + c) * SEQ;
; #pragma unroll 4
;             for (int j = 0; j < 8; ++j) { const int e0 = 4 * tid + 2048 * j; f32x4 v;
;                 if (e0 < SEQ) v = *(const f32x4*)(ff + e0);
;                 else { const int d0 = 16384 - e0; const f32x4 a = *(const f32x4*)(fb + d0 - 4); const float bq = d0 < SEQ ? fb[d0] : 0.f; v = (f32x4){bq, a[3], a[2], a[1]}; }
;                 ssq += (v[0] * v[0] + v[1] * v[1]) + (v[2] * v[2] + v[3] * v[3]);
;                 f32x2* xp = X + fidx(e0); *(f32x4*)xp = (f32x4){v[0], 0.f, v[1], 0.f}; *(f32x4*)(xp + 2) = (f32x4){v[2], 0.f, v[3], 0.f}; }
.LBB0_251:
	s_and_b64 vcc, exec, s[0:1]
	s_cbranch_vccz .LBB0_278
	s_mov_b32 s24, 0
	v_mov_b32_e32 v138, v247
	v_mov_b32_e32 v170, v246
	v_mov_b32_e32 v172, v245
	v_ashrrev_i32_e32 v173, 31, v245
	v_lshl_add_u64 v[0:1], v[172:173], 2, s[74:75]
	v_add_u32_e32 v172, 0xffffe000, v246
	v_ashrrev_i32_e32 v173, 31, v172
	global_load_dwordx4 v[30:33], v[0:1], off
	v_lshl_add_u64 v[2:3], v[172:173], 2, s[40:41]
	v_add_co_u32_e32 v0, vcc, 0x2000, v0
	s_nop 1
	v_addc_co_u32_e32 v1, vcc, 0, v1, vcc
	global_load_dwordx4 v[30:33], v[2:3], off offset:-16
	global_load_dwordx4 v[30:33], v[0:1], off
	v_add_co_u32_e32 v2, vcc, 0xffffe000, v2
	s_nop 1
	v_addc_co_u32_e32 v3, vcc, -1, v3, vcc
	v_add_co_u32_e32 v0, vcc, 0x2000, v0
	s_nop 1
	v_addc_co_u32_e32 v1, vcc, 0, v1, vcc
	global_load_dwordx4 v[30:33], v[2:3], off offset:-16
	global_load_dwordx4 v[30:33], v[0:1], off
	v_add_co_u32_e32 v2, vcc, 0xffffe000, v2
	s_nop 1
	v_addc_co_u32_e32 v3, vcc, -1, v3, vcc
	v_add_co_u32_e32 v0, vcc, 0x2000, v0
	s_nop 1
	v_addc_co_u32_e32 v1, vcc, 0, v1, vcc
	global_load_dwordx4 v[30:33], v[2:3], off offset:-16
	global_load_dwordx4 v[30:33], v[0:1], off
	v_add_co_u32_e32 v2, vcc, 0xffffe000, v2
	s_nop 1
	v_addc_co_u32_e32 v3, vcc, -1, v3, vcc
	s_nop 0
	global_load_dwordx4 v[30:33], v[2:3], off offset:-16
	s_branch .LBB0_254
